# also aligned the attention step-loop heads and the SSD chunk/head loop heads to 64 bytes
# speedup vs baseline: 1.0021x; 1.0021x over previous
.LBB0_1030:
	s_lshl_b32 s0, s68, 1
	s_and_b32 s46, s0, 0x700
	s_ashr_i32 s0, s73, 6
	s_ashr_i32 s1, s0, 31
	s_lshl_b32 s2, s73, 8
	s_and_b32 s2, s2, 0x700
	s_lshl_b64 s[62:63], s[0:1], 11
	s_or_b32 s62, s62, s2
	s_mul_i32 s1, s63, 0x2c00
	s_mul_hi_u32 s2, s62, 0x2c00
	s_add_i32 s2, s2, s1
	s_mul_i32 s1, s62, 0x2c00
	s_add_u32 s1, s6, s1
	s_addc_u32 s33, s7, s2
	s_lshl_b32 s2, s73, 4
	s_and_b32 s2, s2, 0x380
	s_lshl_b32 s36, s2, 1
	s_add_u32 s42, s1, s36
	s_addc_u32 s43, s33, 0
	s_mul_i32 s48, s0, 0x1600000
	s_mul_hi_i32 s47, s0, 0x1600000
	s_add_u32 s0, s6, s48
	s_addc_u32 s1, s7, s47
	s_add_u32 s40, s0, s36
	s_addc_u32 s41, s1, 0
	s_add_u32 s36, s40, 0x800
	s_addc_u32 s37, s41, 0
	s_add_u32 s38, s40, 0x1000
	v_readfirstlane_b32 s44, v182
	s_addc_u32 s39, s41, 0
	s_lshr_b32 s49, s44, 6
	s_and_b32 s0, s44, 0x3fffffc0
	s_lshl_b32 s0, s0, 2
	v_lshl_or_b32 v2, s49, 5, v131
	v_mov_b64_e32 v[0:1], s[42:43]
	s_add_i32 s50, s0, 0
	v_mad_u64_u32 v[0:1], s[0:1], v2, s70, v[0:1]
	s_lshr_b32 s0, s44, 5
	v_lshlrev_b32_e32 v132, 1, v130
	v_and_or_b32 v2, s0, 4, v185
	s_lshr_b32 s0, s44, 4
	v_lshl_add_u64 v[0:1], v[0:1], 0, v[132:133]
	s_lshl_b32 s33, s49, 10
	s_and_b32 s0, s0, 0x7ffff0
	global_load_dword v210, v133, s[84:85]
	global_load_dwordx4 v[108:111], v[0:1], off
	global_load_dwordx4 v[104:107], v[0:1], off offset:32
	global_load_dwordx4 v[100:103], v[0:1], off offset:64
	global_load_dwordx4 v[96:99], v[0:1], off offset:96
	v_lshl_or_b32 v1, s49, 3, v183
	v_or_b32_e32 v0, s0, v2
	s_add_i32 s0, s33, 0x2000
	s_lshr_b32 s0, s0, 8
	v_mul_lo_u32 v1, v1, s9
	s_and_b32 s74, s44, 64
	s_and_b32 s0, s0, 0x7ffff0
	v_or_b32_e32 v4, v1, v184
	v_mov_b32_e32 v5, v133
	v_or_b32_e32 v3, s74, v186
	v_mul_u32_u24_e32 v54, 0x1600, v0
	v_or_b32_e32 v2, s0, v2
	v_lshlrev_b64 v[4:5], 1, v[4:5]
	v_or_b32_e32 v0, v54, v3
	v_mul_u32_u24_e32 v55, 0x1600, v2
	v_lshl_add_u64 v[6:7], s[40:41], 0, v[4:5]
	s_mov_b64 s[0:1], 0x800
	s_add_i32 s51, s33, 0
	v_mov_b32_e32 v1, v133
	v_or_b32_e32 v2, v55, v3
	v_lshl_add_u64 v[6:7], v[6:7], 0, s[0:1]
	s_add_i32 m0, s51, 0xc000
	v_lshlrev_b64 v[48:49], 1, v[0:1]
	v_mov_b32_e32 v3, v133
	global_load_lds_dwordx4 v[6:7], off
	v_lshl_add_u64 v[0:1], s[38:39], 0, v[48:49]
	s_mov_b32 m0, s51
	v_lshlrev_b64 v[50:51], 1, v[2:3]
	global_load_lds_dwordx4 v[0:1], off
	v_lshl_add_u64 v[0:1], s[38:39], 0, v[50:51]
	s_add_i32 m0, s51, 0x2000
	s_add_i32 s50, s50, 0x12000
	global_load_lds_dwordx4 v[0:1], off
	s_add_i32 m0, s51, 0xe000
	v_lshl_add_u64 v[52:53], s[36:37], 0, v[4:5]
	s_mov_b64 s[0:1], 0xb0000
	s_add_u32 s44, s40, 0xb1000
	v_lshl_add_u64 v[0:1], v[52:53], 0, s[0:1]
	s_addc_u32 s45, s41, 0
	global_load_lds_dwordx4 v[0:1], off
	v_lshl_add_u64 v[0:1], s[44:45], 0, v[48:49]
	s_add_i32 m0, s51, 0x4000
	s_mov_b32 s75, 1
	global_load_lds_dwordx4 v[0:1], off
	v_lshl_add_u64 v[0:1], s[44:45], 0, v[50:51]
	s_add_i32 m0, s51, 0x6000
	s_nop 0
	global_load_lds_dwordx4 v[0:1], off
	s_waitcnt vmcnt(0)
	s_barrier
	s_setprio 1
	v_add_u32_e32 v211, v190, v191
	ds_read_b128 v[0:3], v211 offset:49152
	ds_read_b128 v[4:7], v211 offset:53248
	v_add_u32_e32 v212, v190, v192
	v_add_u32_e32 v213, v190, v193
	v_add_u32_e32 v214, v190, v194
	s_waitcnt vmcnt(0) lgkmcnt(0)
	v_mfma_f32_32x32x16_bf16 v[32:47], v[0:3], v[108:111], 0
	v_mfma_f32_32x32x16_bf16 v[16:31], v[4:7], v[108:111], 0
	ds_read_b128 v[0:3], v212 offset:49152
	ds_read_b128 v[4:7], v212 offset:53248
	s_waitcnt lgkmcnt(1)
	v_mfma_f32_32x32x16_bf16 v[32:47], v[0:3], v[104:107], v[32:47]
	s_waitcnt lgkmcnt(0)
	v_mfma_f32_32x32x16_bf16 v[16:31], v[4:7], v[104:107], v[16:31]
	ds_read_b128 v[0:3], v213 offset:49152
	ds_read_b128 v[4:7], v213 offset:53248
	s_waitcnt lgkmcnt(1)
	v_mfma_f32_32x32x16_bf16 v[32:47], v[0:3], v[100:103], v[32:47]
	ds_read_b128 v[0:3], v214 offset:49152
	ds_read_b128 v[56:59], v214 offset:53248
	s_waitcnt lgkmcnt(2)
	v_mfma_f32_32x32x16_bf16 v[16:31], v[4:7], v[100:103], v[16:31]
	s_waitcnt lgkmcnt(1)
	v_mfma_f32_32x32x16_bf16 v[32:47], v[0:3], v[96:99], v[32:47]
	v_mov_b64_e32 v[0:1], s[16:17]
	v_mov_b64_e32 v[2:3], s[18:19]
	v_mov_b64_e32 v[4:5], s[20:21]
	v_mov_b64_e32 v[6:7], s[22:23]
	v_mov_b64_e32 v[8:9], s[24:25]
	v_mov_b64_e32 v[10:11], s[26:27]
	v_mov_b64_e32 v[12:13], s[28:29]
	s_waitcnt lgkmcnt(0)
	v_mfma_f32_32x32x16_bf16 v[16:31], v[56:59], v[96:99], v[16:31]
	v_mov_b64_e32 v[14:15], s[30:31]
	s_setprio 0
	s_nop 0
	v_max_f32_e32 v56, v33, v33
	v_max_f32_e32 v57, v32, v32
	v_max_f32_e32 v56, v57, v56
	v_max3_f32 v56, v56, v34, v35
	v_max3_f32 v56, v56, v36, v37
	v_max3_f32 v56, v56, v38, v39
	v_max3_f32 v56, v56, v40, v41
	v_max3_f32 v56, v56, v42, v43
	v_max3_f32 v56, v56, v44, v45
	v_max3_f32 v56, v56, v46, v47
	v_max3_f32 v56, v56, v16, v17
	v_max3_f32 v56, v56, v18, v19
	v_max3_f32 v56, v56, v20, v21
	v_max3_f32 v56, v56, v22, v23
	v_max3_f32 v56, v56, v24, v25
	v_max3_f32 v56, v56, v26, v27
	v_max3_f32 v56, v56, v28, v29
	v_max3_f32 v56, v56, v30, v31
	v_mov_b32_e32 v57, v56
	s_nop 1
	v_permlane32_swap_b32_e32 v56, v57
	v_max_f32_e32 v57, v57, v57
	v_max_f32_e32 v56, v56, v56
	v_max_f32_e32 v56, v56, v57
	v_add_f32_e32 v57, 0x7149f2ca, v56
	v_cmp_ge_f32_e32 vcc, s71, v57
	s_cmp_eq_u64 vcc, exec
	s_cselect_b64 vcc, -1, 0
	s_add_i32 m0, s51, 0x10000
	s_mov_b64 s[0:1], 0x160000
	s_add_u32 s66, s40, 0x161000
	v_lshl_add_u64 v[52:53], v[52:53], 0, s[0:1]
	s_addc_u32 s67, s41, 0
	global_load_lds_dwordx4 v[52:53], off
	v_lshl_add_u64 v[48:49], s[66:67], 0, v[48:49]
	s_add_i32 m0, s51, 0x8000
	v_max_f32_e32 v56, 0xf149f2ca, v56
	global_load_lds_dwordx4 v[48:49], off
	v_lshl_add_u64 v[48:49], s[66:67], 0, v[50:51]
	s_add_i32 m0, s51, 0xa000
	v_cndmask_b32_e32 v218, v56, v208, vcc
	global_load_lds_dwordx4 v[48:49], off
	v_sub_f32_e32 v48, 0xf149f2ca, v56
	v_mul_f32_e32 v48, 0x3e38aa3b, v48
	v_exp_f32_e32 v48, v48
	s_mul_i32 s49, s49, 0xb000
	s_or_b32 s0, s48, s46
	s_add_u32 s64, s84, s0
	v_cndmask_b32_e64 v217, v48, 1.0, vcc
	v_mul_f32_e32 v48, 0xbe38aa3b, v218
	v_mov_b32_e32 v49, v48
	v_fmac_f32_e32 v49, 0x3e38aa3b, v47
	v_fmamk_f32 v32, v32, 0x3e38aa3b, v48
	v_fmamk_f32 v33, v33, 0x3e38aa3b, v48
	v_fmamk_f32 v34, v34, 0x3e38aa3b, v48
	v_fmamk_f32 v35, v35, 0x3e38aa3b, v48
	v_fmamk_f32 v36, v36, 0x3e38aa3b, v48
	v_fmamk_f32 v37, v37, 0x3e38aa3b, v48
	v_fmamk_f32 v38, v38, 0x3e38aa3b, v48
	v_fmamk_f32 v39, v39, 0x3e38aa3b, v48
	v_fmamk_f32 v40, v40, 0x3e38aa3b, v48
	v_fmamk_f32 v41, v41, 0x3e38aa3b, v48
	v_fmamk_f32 v42, v42, 0x3e38aa3b, v48
	v_fmamk_f32 v43, v43, 0x3e38aa3b, v48
	v_fmamk_f32 v44, v44, 0x3e38aa3b, v48
	v_fmamk_f32 v45, v45, 0x3e38aa3b, v48
	v_fmamk_f32 v46, v46, 0x3e38aa3b, v48
	v_pk_fma_f32 v[174:175], v[16:17], s[8:9], v[48:49] op_sel_hi:[1,0,0]
	v_add_u32_e32 v16, s49, v196
	v_mov_b32_e32 v17, v133
	v_exp_f32_e32 v115, v32
	v_exp_f32_e32 v124, v33
	v_exp_f32_e32 v125, v34
	v_exp_f32_e32 v126, v35
	v_exp_f32_e32 v127, v36
	v_exp_f32_e32 v176, v37
	v_exp_f32_e32 v177, v38
	v_exp_f32_e32 v178, v39
	v_exp_f32_e32 v116, v40
	v_exp_f32_e32 v117, v41
	v_exp_f32_e32 v118, v42
	v_exp_f32_e32 v119, v43
	v_exp_f32_e32 v120, v44
	v_exp_f32_e32 v121, v45
	v_exp_f32_e32 v122, v46
	v_exp_f32_e32 v123, v49
	v_lshlrev_b64 v[154:155], 1, v[16:17]
	v_or3_b32 v16, v186, v54, s74
	v_lshlrev_b64 v[156:157], 1, v[16:17]
	v_or3_b32 v16, v186, v55, s74
	v_pk_fma_f32 v[160:161], v[30:31], s[8:9], v[48:49] op_sel_hi:[1,0,0]
	v_pk_fma_f32 v[162:163], v[28:29], s[8:9], v[48:49] op_sel_hi:[1,0,0]
	v_pk_fma_f32 v[164:165], v[26:27], s[8:9], v[48:49] op_sel_hi:[1,0,0]
	v_pk_fma_f32 v[166:167], v[24:25], s[8:9], v[48:49] op_sel_hi:[1,0,0]
	v_pk_fma_f32 v[168:169], v[22:23], s[8:9], v[48:49] op_sel_hi:[1,0,0]
	v_pk_fma_f32 v[170:171], v[20:21], s[8:9], v[48:49] op_sel_hi:[1,0,0]
	v_pk_fma_f32 v[172:173], v[18:19], s[8:9], v[48:49] op_sel_hi:[1,0,0]
	s_addc_u32 s65, s85, s47
	v_lshlrev_b64 v[158:159], 1, v[16:17]
	v_mov_b64_e32 v[30:31], v[14:15]
	v_mov_b64_e32 v[46:47], v[14:15]
	v_mov_b64_e32 v[62:63], v[14:15]
	v_lshl_add_u32 v215, v131, 2, s50
	s_mov_b64 s[46:47], s[64:65]
	v_mov_b64_e32 v[28:29], v[12:13]
	v_mov_b64_e32 v[26:27], v[10:11]
	v_mov_b64_e32 v[24:25], v[8:9]
	v_mov_b64_e32 v[22:23], v[6:7]
	v_mov_b64_e32 v[20:21], v[4:5]
	v_mov_b64_e32 v[18:19], v[2:3]
	v_mov_b64_e32 v[16:17], v[0:1]
	v_mov_b64_e32 v[44:45], v[12:13]
	v_mov_b64_e32 v[42:43], v[10:11]
	v_mov_b64_e32 v[40:41], v[8:9]
	v_mov_b64_e32 v[38:39], v[6:7]
	v_mov_b64_e32 v[36:37], v[4:5]
	v_mov_b64_e32 v[34:35], v[2:3]
	v_mov_b64_e32 v[32:33], v[0:1]
	v_mov_b64_e32 v[60:61], v[12:13]
	v_mov_b64_e32 v[58:59], v[10:11]
	v_mov_b64_e32 v[56:57], v[8:9]
	v_mov_b64_e32 v[54:55], v[6:7]
	v_mov_b64_e32 v[52:53], v[4:5]
	v_mov_b64_e32 v[50:51], v[2:3]
	v_mov_b64_e32 v[48:49], v[0:1]
	s_mov_b32 s76, 0
	s_mov_b32 s74, 1
	v_mov_b32_e32 v216, 0
	.p2align	6

.LBB0_1047:
	v_exp_f32_e32 v80, v80
	v_exp_f32_e32 v81, v81
	v_exp_f32_e32 v96, v64
	v_exp_f32_e32 v97, v65
	v_add_f32_e32 v64, v80, v96
	v_add_f32_e32 v65, v81, v97
	v_exp_f32_e32 v82, v82
	v_exp_f32_e32 v83, v83
	v_add_f32_e32 v64, v64, v82
	v_add_f32_e32 v65, v65, v83
	v_exp_f32_e32 v98, v66
	v_exp_f32_e32 v99, v67
	v_add_f32_e32 v64, v64, v98
	v_add_f32_e32 v65, v65, v99
	v_exp_f32_e32 v84, v84
	v_exp_f32_e32 v85, v85
	v_add_f32_e32 v64, v64, v84
	v_add_f32_e32 v65, v65, v85
	v_exp_f32_e32 v100, v68
	v_exp_f32_e32 v101, v69
	v_add_f32_e32 v64, v64, v100
	v_add_f32_e32 v65, v65, v101
	v_exp_f32_e32 v86, v86
	v_exp_f32_e32 v87, v87
	v_add_f32_e32 v64, v64, v86
	v_add_f32_e32 v65, v65, v87
	v_exp_f32_e32 v102, v70
	v_exp_f32_e32 v103, v71
	v_add_f32_e32 v64, v64, v102
	v_add_f32_e32 v65, v65, v103
	v_exp_f32_e32 v88, v88
	v_exp_f32_e32 v89, v89
	v_add_f32_e32 v64, v64, v88
	v_add_f32_e32 v65, v65, v89
	v_exp_f32_e32 v104, v72
	v_exp_f32_e32 v105, v73
	v_add_f32_e32 v64, v64, v104
	v_add_f32_e32 v65, v65, v105
	v_exp_f32_e32 v90, v90
	v_exp_f32_e32 v91, v91
	v_add_f32_e32 v64, v64, v90
	v_add_f32_e32 v65, v65, v91
	v_exp_f32_e32 v106, v74
	v_exp_f32_e32 v107, v75
	v_add_f32_e32 v64, v64, v106
	v_add_f32_e32 v65, v65, v107
	v_exp_f32_e32 v92, v92
	v_exp_f32_e32 v93, v93
	v_add_f32_e32 v64, v64, v92
	v_add_f32_e32 v65, v65, v93
	v_exp_f32_e32 v108, v76
	v_exp_f32_e32 v109, v77
	v_add_f32_e32 v64, v64, v108
	v_add_f32_e32 v65, v65, v109
	v_exp_f32_e32 v94, v94
	v_exp_f32_e32 v95, v95
	v_add_f32_e32 v64, v64, v94
	v_add_f32_e32 v65, v65, v95
	v_exp_f32_e32 v110, v78
	v_exp_f32_e32 v111, v79
	v_add_f32_e32 v64, v64, v110
	v_add_f32_e32 v65, v65, v111
	v_cvt_pk_bf16_f32 v66, v80, v81
	v_cvt_pk_bf16_f32 v67, v82, v83
	v_cvt_pk_bf16_f32 v68, v84, v85
	v_cvt_pk_bf16_f32 v69, v86, v87
	v_cvt_pk_bf16_f32 v70, v88, v89
	s_nop 0
	v_add_f32_e32 v64, v64, v65
	v_cvt_pk_bf16_f32 v71, v90, v91
	v_cvt_pk_bf16_f32 v72, v92, v93
	v_cvt_pk_bf16_f32 v73, v94, v95
	v_cvt_pk_bf16_f32 v74, v96, v97
	v_cvt_pk_bf16_f32 v75, v98, v99
	s_nop 0
	v_mov_b32_e32 v65, v64
	s_nop 1
	v_permlane32_swap_b32_e32 v64, v65
	v_cvt_pk_bf16_f32 v76, v100, v101
	v_cvt_pk_bf16_f32 v77, v102, v103
	v_cvt_pk_bf16_f32 v78, v104, v105
	v_cvt_pk_bf16_f32 v79, v106, v107
	v_cvt_pk_bf16_f32 v80, v108, v109
	v_cvt_pk_bf16_f32 v81, v110, v111
	v_permlane32_swap_b32_e32 v66, v68
	v_permlane32_swap_b32_e32 v67, v69
	v_permlane32_swap_b32_e32 v70, v72
	v_permlane32_swap_b32_e32 v71, v73
	v_permlane32_swap_b32_e32 v74, v76
	v_permlane32_swap_b32_e32 v75, v77
	v_permlane32_swap_b32_e32 v78, v80
	v_permlane32_swap_b32_e32 v79, v81
	ds_read_b64_tr_b16 v[82:83], v195 offset:0
	ds_read_b64_tr_b16 v[84:85], v195 offset:0x800
	ds_read_b64_tr_b16 v[86:87], v195 offset:0x1000
	ds_read_b64_tr_b16 v[88:89], v195 offset:0x1800
	ds_read_b64_tr_b16 v[90:91], v195 offset:0x2000
	ds_read_b64_tr_b16 v[92:93], v195 offset:0x2800
	ds_read_b64_tr_b16 v[94:95], v195 offset:0x3000
	ds_read_b64_tr_b16 v[96:97], v195 offset:0x3800
	s_setprio 1
	s_waitcnt lgkmcnt(6)
	v_mfma_f32_32x32x16_bf16 v[48:63], v[66:69], v[82:85], v[48:63]
	s_waitcnt lgkmcnt(4)
	v_mfma_f32_32x32x16_bf16 v[48:63], v[70:73], v[86:89], v[48:63]
	s_waitcnt lgkmcnt(2)
	v_mfma_f32_32x32x16_bf16 v[48:63], v[74:77], v[90:93], v[48:63]
	s_waitcnt lgkmcnt(0)
	v_mfma_f32_32x32x16_bf16 v[48:63], v[78:81], v[94:97], v[48:63]
	s_setprio 0
	ds_read_b64_tr_b16 v[82:83], v195 offset:0x200
	ds_read_b64_tr_b16 v[84:85], v195 offset:0xa00
	ds_read_b64_tr_b16 v[86:87], v195 offset:0x1200
	ds_read_b64_tr_b16 v[88:89], v195 offset:0x1a00
	ds_read_b64_tr_b16 v[90:91], v195 offset:0x2200
	ds_read_b64_tr_b16 v[92:93], v195 offset:0x2a00
	ds_read_b64_tr_b16 v[94:95], v195 offset:0x3200
	ds_read_b64_tr_b16 v[96:97], v195 offset:0x3a00
	s_setprio 1
	s_waitcnt lgkmcnt(6)
	v_mfma_f32_32x32x16_bf16 v[32:47], v[66:69], v[82:85], v[32:47]
	s_waitcnt lgkmcnt(4)
	v_mfma_f32_32x32x16_bf16 v[32:47], v[70:73], v[86:89], v[32:47]
	s_waitcnt lgkmcnt(2)
	v_mfma_f32_32x32x16_bf16 v[32:47], v[74:77], v[90:93], v[32:47]
	s_waitcnt lgkmcnt(0)
	v_mfma_f32_32x32x16_bf16 v[32:47], v[78:81], v[94:97], v[32:47]
	s_setprio 0
	ds_read_b64_tr_b16 v[82:83], v195 offset:0x400
	ds_read_b64_tr_b16 v[84:85], v195 offset:0xc00
	ds_read_b64_tr_b16 v[86:87], v195 offset:0x1400
	ds_read_b64_tr_b16 v[88:89], v195 offset:0x1c00
	ds_read_b64_tr_b16 v[90:91], v195 offset:0x2400
	ds_read_b64_tr_b16 v[92:93], v195 offset:0x2c00
	ds_read_b64_tr_b16 v[94:95], v195 offset:0x3400
	ds_read_b64_tr_b16 v[96:97], v195 offset:0x3c00
	s_setprio 1
	s_waitcnt lgkmcnt(6)
	v_mfma_f32_32x32x16_bf16 v[16:31], v[66:69], v[82:85], v[16:31]
	s_waitcnt lgkmcnt(4)
	v_mfma_f32_32x32x16_bf16 v[16:31], v[70:73], v[86:89], v[16:31]
	s_waitcnt lgkmcnt(2)
	v_mfma_f32_32x32x16_bf16 v[16:31], v[74:77], v[90:93], v[16:31]
	s_waitcnt lgkmcnt(0)
	v_mfma_f32_32x32x16_bf16 v[16:31], v[78:81], v[94:97], v[16:31]
	s_setprio 0
	ds_read_b64_tr_b16 v[82:83], v195 offset:0x600
	ds_read_b64_tr_b16 v[84:85], v195 offset:0xe00
	ds_read_b64_tr_b16 v[86:87], v195 offset:0x1600
	ds_read_b64_tr_b16 v[88:89], v195 offset:0x1e00
	ds_read_b64_tr_b16 v[90:91], v195 offset:0x2600
	ds_read_b64_tr_b16 v[92:93], v195 offset:0x2e00
	ds_read_b64_tr_b16 v[94:95], v195 offset:0x3600
	ds_read_b64_tr_b16 v[96:97], v195 offset:0x3e00
	s_setprio 1
	s_waitcnt lgkmcnt(6)
	v_mfma_f32_32x32x16_bf16 v[0:15], v[66:69], v[82:85], v[0:15]
	s_waitcnt lgkmcnt(4)
	v_mfma_f32_32x32x16_bf16 v[0:15], v[70:73], v[86:89], v[0:15]
	s_waitcnt lgkmcnt(2)
	v_mfma_f32_32x32x16_bf16 v[0:15], v[74:77], v[90:93], v[0:15]
	s_waitcnt lgkmcnt(0)
	v_mfma_f32_32x32x16_bf16 v[0:15], v[78:81], v[94:97], v[0:15]
	s_setprio 0
	s_and_saveexec_b64 s[0:1], s[4:5]
	v_add_f32_e32 v66, v113, v114
	v_fmac_f32_e32 v66, v216, v112
	v_add_f32_e32 v64, v64, v65
	v_fmac_f32_e32 v64, v66, v115
	ds_write_b32 v215, v64
	s_or_b64 exec, exec, s[0:1]
	s_waitcnt lgkmcnt(0)
	v_add_u32_e32 v72, s50, v188
	ds_read_b128 v[64:67], v72
	ds_read_b128 v[68:71], v72 offset:32
	v_add_u32_e32 v222, v141, v139
	v_add_u32_e32 v221, v141, v143
	v_add_u32_e32 v220, v145, v139
	s_waitcnt lgkmcnt(0)
	v_rcp_f32_e32 v73, v64
	v_rcp_f32_e32 v74, v65
	v_rcp_f32_e32 v75, v66
	v_rcp_f32_e32 v76, v67
	v_mul_f32_e32 v48, v48, v73
	v_mul_f32_e32 v32, v32, v73
	v_mul_f32_e32 v16, v16, v73
	v_mul_f32_e32 v0, v0, v73
	v_rcp_f32_e32 v77, v68
	ds_read_b128 v[64:67], v72 offset:64
	v_rcp_f32_e32 v78, v69
	v_rcp_f32_e32 v79, v70
	v_rcp_f32_e32 v80, v71
	ds_read_b128 v[68:71], v72 offset:96
	s_waitcnt vmcnt(0) lgkmcnt(0)
	s_barrier
	v_cvt_pk_bf16_f32 v48, v48, v133
	ds_write_b16 v222, v48
	v_cvt_pk_bf16_f32 v32, v32, v133
	ds_write_b16 v221, v32
	v_cvt_pk_bf16_f32 v16, v16, v133
	ds_write_b16 v222, v16 offset:128
	v_cvt_pk_bf16_f32 v0, v0, v133
	ds_write_b16 v221, v0 offset:128
	v_mul_f32_e32 v0, v49, v74
	v_cvt_pk_bf16_f32 v0, v0, v133
	ds_write_b16 v220, v0 offset:256
	v_mul_f32_e32 v0, v33, v74
	v_cvt_pk_bf16_f32 v0, v0, v133
	v_add_u32_e32 v219, v145, v143
	ds_write_b16 v219, v0 offset:256
	v_mul_f32_e32 v0, v17, v74
	v_cvt_pk_bf16_f32 v0, v0, v133
	ds_write_b16 v220, v0 offset:384
	v_mul_f32_e32 v0, v1, v74
	v_cvt_pk_bf16_f32 v0, v0, v133
	ds_write_b16 v219, v0 offset:384
	v_mul_f32_e32 v0, v50, v75
	v_cvt_pk_bf16_f32 v0, v0, v133
	v_add_u32_e32 v218, v147, v139
	ds_write_b16 v218, v0 offset:512
	v_mul_f32_e32 v0, v34, v75
	v_cvt_pk_bf16_f32 v0, v0, v133
	v_add_u32_e32 v217, v147, v143
	ds_write_b16 v217, v0 offset:512
	v_mul_f32_e32 v0, v18, v75
	v_cvt_pk_bf16_f32 v0, v0, v133
	ds_write_b16 v218, v0 offset:640
	v_mul_f32_e32 v0, v2, v75
	v_cvt_pk_bf16_f32 v0, v0, v133
	ds_write_b16 v217, v0 offset:640
	v_mul_f32_e32 v0, v51, v76
	v_cvt_pk_bf16_f32 v0, v0, v133
	v_add_u32_e32 v215, v149, v139
	ds_write_b16 v215, v0 offset:768
	v_mul_f32_e32 v0, v35, v76
	v_cvt_pk_bf16_f32 v0, v0, v133
	v_add_u32_e32 v216, v149, v143
	ds_write_b16 v216, v0 offset:768
	v_mul_f32_e32 v0, v19, v76
	v_cvt_pk_bf16_f32 v0, v0, v133
	ds_write_b16 v215, v0 offset:896
	v_mul_f32_e32 v0, v3, v76
	v_cvt_pk_bf16_f32 v0, v0, v133
	ds_write_b16 v216, v0 offset:896
	v_mul_f32_e32 v0, v52, v77
	v_cvt_pk_bf16_f32 v0, v0, v133
	ds_write_b16 v222, v0 offset:2176
	v_mul_f32_e32 v0, v36, v77
	v_cvt_pk_bf16_f32 v0, v0, v133
	ds_write_b16 v221, v0 offset:2176
	v_mul_f32_e32 v0, v20, v77
	v_cvt_pk_bf16_f32 v0, v0, v133
	ds_write_b16 v222, v0 offset:2048
	v_mul_f32_e32 v0, v4, v77
	v_cvt_pk_bf16_f32 v0, v0, v133
	ds_write_b16 v221, v0 offset:2048
	v_mul_f32_e32 v0, v53, v78
	v_cvt_pk_bf16_f32 v0, v0, v133
	ds_write_b16 v220, v0 offset:2432
	v_mul_f32_e32 v0, v37, v78
	v_cvt_pk_bf16_f32 v0, v0, v133
	ds_write_b16 v219, v0 offset:2432
	v_mul_f32_e32 v0, v21, v78
	v_cvt_pk_bf16_f32 v0, v0, v133
	ds_write_b16 v220, v0 offset:2304
	v_mul_f32_e32 v0, v5, v78
	v_cvt_pk_bf16_f32 v0, v0, v133
	ds_write_b16 v219, v0 offset:2304
	v_mul_f32_e32 v0, v54, v79
	v_cvt_pk_bf16_f32 v0, v0, v133
	ds_write_b16 v218, v0 offset:2688
	v_mul_f32_e32 v0, v38, v79
	v_cvt_pk_bf16_f32 v0, v0, v133
	ds_write_b16 v217, v0 offset:2688
	v_mul_f32_e32 v0, v22, v79
	v_cvt_pk_bf16_f32 v0, v0, v133
	ds_write_b16 v218, v0 offset:2560
	v_mul_f32_e32 v0, v6, v79
	v_cvt_pk_bf16_f32 v0, v0, v133
	ds_write_b16 v217, v0 offset:2560
	v_mul_f32_e32 v0, v55, v80
	v_cvt_pk_bf16_f32 v0, v0, v133
	ds_write_b16 v215, v0 offset:2944
	v_mul_f32_e32 v0, v39, v80
	v_cvt_pk_bf16_f32 v0, v0, v133
	v_rcp_f32_e32 v64, v64
	ds_write_b16 v216, v0 offset:2944
	v_mul_f32_e32 v0, v23, v80
	v_cvt_pk_bf16_f32 v0, v0, v133
	ds_write_b16 v215, v0 offset:2816
	v_mul_f32_e32 v0, v7, v80
	v_cvt_pk_bf16_f32 v0, v0, v133
	ds_write_b16 v216, v0 offset:2816
	v_mul_f32_e32 v0, v56, v64
	v_cvt_pk_bf16_f32 v0, v0, v133
	ds_write_b16 v222, v0 offset:4096
	v_mul_f32_e32 v0, v40, v64
	v_cvt_pk_bf16_f32 v0, v0, v133
	v_rcp_f32_e32 v65, v65
	ds_write_b16 v221, v0 offset:4096
	v_mul_f32_e32 v0, v24, v64
	v_cvt_pk_bf16_f32 v0, v0, v133
	ds_write_b16 v222, v0 offset:4224
	v_mul_f32_e32 v0, v8, v64
	v_cvt_pk_bf16_f32 v0, v0, v133
	ds_write_b16 v221, v0 offset:4224
	v_mul_f32_e32 v0, v57, v65
	v_cvt_pk_bf16_f32 v0, v0, v133
	ds_write_b16 v220, v0 offset:4352
	v_mul_f32_e32 v0, v41, v65
	v_cvt_pk_bf16_f32 v0, v0, v133
	v_rcp_f32_e32 v66, v66
	ds_write_b16 v219, v0 offset:4352
	v_mul_f32_e32 v0, v25, v65
	v_cvt_pk_bf16_f32 v0, v0, v133
	ds_write_b16 v220, v0 offset:4480
	v_mul_f32_e32 v0, v9, v65
	v_cvt_pk_bf16_f32 v0, v0, v133
	ds_write_b16 v219, v0 offset:4480
	v_mul_f32_e32 v0, v58, v66
	v_cvt_pk_bf16_f32 v0, v0, v133
	ds_write_b16 v218, v0 offset:4608
	v_mul_f32_e32 v0, v42, v66
	v_cvt_pk_bf16_f32 v0, v0, v133
	v_rcp_f32_e32 v67, v67
	ds_write_b16 v217, v0 offset:4608
	v_mul_f32_e32 v0, v26, v66
	v_cvt_pk_bf16_f32 v0, v0, v133
	ds_write_b16 v218, v0 offset:4736
	v_mul_f32_e32 v0, v10, v66
	v_cvt_pk_bf16_f32 v0, v0, v133
	ds_write_b16 v217, v0 offset:4736
	v_mul_f32_e32 v0, v59, v67
	v_cvt_pk_bf16_f32 v0, v0, v133
	ds_write_b16 v215, v0 offset:4864
	v_mul_f32_e32 v0, v43, v67
	v_cvt_pk_bf16_f32 v0, v0, v133
	v_rcp_f32_e32 v68, v68
	ds_write_b16 v216, v0 offset:4864
	v_mul_f32_e32 v0, v27, v67
	v_cvt_pk_bf16_f32 v0, v0, v133
	ds_write_b16 v215, v0 offset:4992
	v_mul_f32_e32 v0, v11, v67
	v_cvt_pk_bf16_f32 v0, v0, v133
	ds_write_b16 v216, v0 offset:4992
	v_mul_f32_e32 v0, v60, v68
	v_cvt_pk_bf16_f32 v0, v0, v133
	ds_write_b16 v222, v0 offset:6272
	v_mul_f32_e32 v0, v44, v68
	v_cvt_pk_bf16_f32 v0, v0, v133
	v_rcp_f32_e32 v69, v69
	ds_write_b16 v221, v0 offset:6272
	v_mul_f32_e32 v0, v28, v68
	v_cvt_pk_bf16_f32 v0, v0, v133
	ds_write_b16 v222, v0 offset:6144
	v_mul_f32_e32 v0, v12, v68
	v_cvt_pk_bf16_f32 v0, v0, v133
	ds_write_b16 v221, v0 offset:6144
	v_mul_f32_e32 v0, v61, v69
	v_cvt_pk_bf16_f32 v0, v0, v133
	ds_write_b16 v220, v0 offset:6528
	v_mul_f32_e32 v0, v45, v69
	v_cvt_pk_bf16_f32 v0, v0, v133
	v_rcp_f32_e32 v70, v70
	ds_write_b16 v219, v0 offset:6528
	v_mul_f32_e32 v0, v29, v69
	v_cvt_pk_bf16_f32 v0, v0, v133
	ds_write_b16 v220, v0 offset:6400
	v_mul_f32_e32 v0, v13, v69
	v_cvt_pk_bf16_f32 v0, v0, v133
	ds_write_b16 v219, v0 offset:6400
	v_mul_f32_e32 v0, v62, v70
	v_cvt_pk_bf16_f32 v0, v0, v133
	ds_write_b16 v218, v0 offset:6784
	v_mul_f32_e32 v0, v46, v70
	v_cvt_pk_bf16_f32 v0, v0, v133
	v_rcp_f32_e32 v71, v71
	ds_write_b16 v217, v0 offset:6784
	v_mul_f32_e32 v0, v30, v70
	v_cvt_pk_bf16_f32 v0, v0, v133
	ds_write_b16 v218, v0 offset:6656
	v_mul_f32_e32 v0, v14, v70
	v_cvt_pk_bf16_f32 v0, v0, v133
	ds_write_b16 v217, v0 offset:6656
	v_mul_f32_e32 v0, v63, v71
	v_cvt_pk_bf16_f32 v0, v0, v133
	ds_write_b16 v215, v0 offset:7040
	v_mul_f32_e32 v0, v47, v71
	v_cvt_pk_bf16_f32 v0, v0, v133
	ds_write_b16 v216, v0 offset:7040
	v_mul_f32_e32 v0, v31, v71
	v_cvt_pk_bf16_f32 v0, v0, v133
	ds_write_b16 v215, v0 offset:6912
	v_mul_f32_e32 v0, v15, v71
	v_readfirstlane_b32 s33, v182
	v_cvt_pk_bf16_f32 v0, v0, v133
	s_lshr_b32 s0, s33, 6
	ds_write_b16 v216, v0 offset:6912
	v_lshl_or_b32 v2, s0, 5, v131
	v_mov_b64_e32 v[0:1], s[42:43]
	v_mad_u64_u32 v[0:1], s[42:43], v2, s70, v[0:1]
	s_lshr_b32 s42, s33, 5
	s_nop 0
	v_and_or_b32 v2, s42, 4, v185
	s_lshr_b32 s42, s33, 4
	v_lshl_add_u64 v[0:1], v[0:1], 0, v[132:133]
	s_lshl_b32 s74, s0, 10
	s_and_b32 s42, s42, 0x7ffff0
	global_load_dwordx4 v[108:111], v[0:1], off offset:128
	global_load_dwordx4 v[104:107], v[0:1], off offset:160
	global_load_dwordx4 v[100:103], v[0:1], off offset:192
	global_load_dwordx4 v[96:99], v[0:1], off offset:224
	v_lshl_or_b32 v1, s0, 3, v183
	v_or_b32_e32 v0, s42, v2
	s_add_i32 s42, s74, 0x2000
	s_lshr_b32 s42, s42, 8
	v_mul_lo_u32 v1, v1, s9
	s_and_b32 s1, s33, 64
	s_and_b32 s42, s42, 0x7ffff0
	v_or_b32_e32 v132, v1, v184
	v_or_b32_e32 v3, s1, v186
	v_mul_u32_u24_e32 v58, 0x1600, v0
	v_or_b32_e32 v2, s42, v2
	v_lshlrev_b64 v[4:5], 1, v[132:133]
	v_or_b32_e32 v0, v58, v3
	v_mul_u32_u24_e32 v59, 0x1600, v2
	v_lshl_add_u64 v[6:7], s[40:41], 0, v[4:5]
	s_add_i32 s75, s74, 0
	v_mov_b32_e32 v1, v133
	v_or_b32_e32 v2, v59, v3
	v_lshl_add_u64 v[6:7], v[6:7], 0, s[52:53]
	s_add_i32 m0, s75, 0xc000
	v_lshlrev_b64 v[52:53], 1, v[0:1]
	v_mov_b32_e32 v3, v133
	global_load_lds_dwordx4 v[6:7], off
	v_lshl_add_u64 v[0:1], s[38:39], 0, v[52:53]
	s_mov_b32 m0, s75
	v_lshlrev_b64 v[54:55], 1, v[2:3]
	global_load_lds_dwordx4 v[0:1], off
	v_lshl_add_u64 v[0:1], s[38:39], 0, v[54:55]
	s_add_i32 m0, s75, 0x2000
	v_lshl_add_u64 v[56:57], s[36:37], 0, v[4:5]
	global_load_lds_dwordx4 v[0:1], off
	v_lshl_add_u64 v[0:1], v[56:57], 0, s[54:55]
	s_add_i32 m0, s75, 0xe000
	s_and_b32 s33, s33, 0x3fffffc0
	global_load_lds_dwordx4 v[0:1], off
	v_lshl_add_u64 v[0:1], s[44:45], 0, v[52:53]
	s_add_i32 m0, s75, 0x4000
	s_lshl_b32 s33, s33, 2
	global_load_lds_dwordx4 v[0:1], off
	v_lshl_add_u64 v[0:1], s[44:45], 0, v[54:55]
	s_add_i32 m0, s75, 0x6000
	s_add_i32 s33, s33, 0
	global_load_lds_dwordx4 v[0:1], off
	s_waitcnt vmcnt(0)
	s_barrier
	s_mov_b32 s36, 0
	s_add_i32 s33, s33, 0x12000
	s_mov_b32 s76, 1
	s_setprio 1
	ds_read_b128 v[0:3], v211 offset:49152
	ds_read_b128 v[4:7], v211 offset:53248
	s_mov_b32 s37, s36
	s_mov_b32 s38, s36
	s_mov_b32 s39, s36
	s_waitcnt vmcnt(0) lgkmcnt(0)
	v_mfma_f32_32x32x16_bf16 v[32:47], v[0:3], v[108:111], 0
	s_mov_b32 s40, s36
	s_mov_b32 s41, s36
	s_mov_b32 s42, s36
	s_mov_b32 s43, s36
	s_mov_b32 s44, s36
	s_mov_b32 s45, s36
	s_mov_b32 s46, s36
	v_mfma_f32_32x32x16_bf16 v[16:31], v[4:7], v[108:111], 0
	ds_read_b128 v[0:3], v212 offset:49152
	ds_read_b128 v[4:7], v212 offset:53248
	s_mov_b32 s47, s36
	s_mov_b32 s48, s36
	s_mov_b32 s49, s36
	s_mov_b32 s50, s36
	s_mov_b32 s51, s36
	s_waitcnt lgkmcnt(1)
	v_mfma_f32_32x32x16_bf16 v[32:47], v[0:3], v[104:107], v[32:47]
	s_waitcnt lgkmcnt(0)
	v_mfma_f32_32x32x16_bf16 v[16:31], v[4:7], v[104:107], v[16:31]
	ds_read_b128 v[0:3], v213 offset:49152
	ds_read_b128 v[4:7], v213 offset:53248
	ds_read_b128 v[48:51], v214 offset:53248
	s_waitcnt lgkmcnt(2)
	v_mfma_f32_32x32x16_bf16 v[32:47], v[0:3], v[100:103], v[32:47]
	ds_read_b128 v[0:3], v214 offset:49152
	s_waitcnt lgkmcnt(2)
	v_mfma_f32_32x32x16_bf16 v[16:31], v[4:7], v[100:103], v[16:31]
	s_waitcnt lgkmcnt(0)
	v_mfma_f32_32x32x16_bf16 v[32:47], v[0:3], v[96:99], v[32:47]
	v_mov_b64_e32 v[0:1], s[36:37]
	v_mov_b64_e32 v[2:3], s[38:39]
	v_mov_b64_e32 v[4:5], s[40:41]
	v_mov_b64_e32 v[6:7], s[42:43]
	v_mov_b64_e32 v[8:9], s[44:45]
	v_mov_b64_e32 v[10:11], s[46:47]
	v_mov_b64_e32 v[12:13], s[48:49]
	v_mfma_f32_32x32x16_bf16 v[16:31], v[48:51], v[96:99], v[16:31]
	v_mov_b64_e32 v[14:15], s[50:51]
	s_setprio 0
	s_nop 1
	v_max_f32_e32 v48, v33, v33
	v_max_f32_e32 v49, v32, v32
	v_max_f32_e32 v48, v49, v48
	v_max3_f32 v48, v48, v34, v35
	v_max3_f32 v48, v48, v36, v37
	v_max3_f32 v48, v48, v38, v39
	v_max3_f32 v48, v48, v40, v41
	v_max3_f32 v48, v48, v42, v43
	v_max3_f32 v48, v48, v44, v45
	v_max3_f32 v48, v48, v46, v47
	v_max3_f32 v48, v48, v16, v17
	v_max3_f32 v48, v48, v18, v19
	v_max3_f32 v48, v48, v20, v21
	v_max3_f32 v48, v48, v22, v23
	v_max3_f32 v48, v48, v24, v25
	v_max3_f32 v48, v48, v26, v27
	v_max3_f32 v48, v48, v28, v29
	v_max3_f32 v48, v48, v30, v31
	v_mov_b32_e32 v49, v48
	s_nop 1
	v_permlane32_swap_b32_e32 v48, v49
	v_max_f32_e32 v49, v49, v49
	v_max_f32_e32 v48, v48, v48
	v_max_f32_e32 v48, v48, v49
	v_add_f32_e32 v49, 0x7149f2ca, v48
	v_cmp_ge_f32_e32 vcc, s71, v49
	s_cmp_eq_u64 vcc, exec
	v_max_f32_e32 v50, 0xf149f2ca, v48
	s_cselect_b64 vcc, -1, 0
	v_lshl_add_u64 v[48:49], v[56:57], 0, s[56:57]
	s_add_i32 m0, s75, 0x10000
	v_cndmask_b32_e32 v227, v50, v208, vcc
	global_load_lds_dwordx4 v[48:49], off
	v_lshl_add_u64 v[48:49], s[66:67], 0, v[52:53]
	s_add_i32 m0, s75, 0x8000
	s_mul_i32 s0, s0, 0xb000
	global_load_lds_dwordx4 v[48:49], off
	v_lshl_add_u64 v[48:49], s[66:67], 0, v[54:55]
	s_add_i32 m0, s75, 0xa000
	v_add_u32_e32 v132, s0, v196
	global_load_lds_dwordx4 v[48:49], off
	v_sub_f32_e32 v48, 0xf149f2ca, v50
	v_mul_f32_e32 v48, 0x3e38aa3b, v48
	v_exp_f32_e32 v48, v48
	v_lshlrev_b64 v[154:155], 1, v[132:133]
	v_or3_b32 v132, v186, v58, s1
	v_lshlrev_b64 v[156:157], 1, v[132:133]
	v_cndmask_b32_e64 v224, v48, 1.0, vcc
	v_mul_f32_e32 v48, 0xbe38aa3b, v227
	v_mov_b32_e32 v49, v48
	v_fmamk_f32 v32, v32, 0x3e38aa3b, v48
	v_fmamk_f32 v33, v33, 0x3e38aa3b, v48
	v_fmamk_f32 v34, v34, 0x3e38aa3b, v48
	v_fmamk_f32 v35, v35, 0x3e38aa3b, v48
	v_fmamk_f32 v36, v36, 0x3e38aa3b, v48
	v_fmamk_f32 v37, v37, 0x3e38aa3b, v48
	v_fmamk_f32 v38, v38, 0x3e38aa3b, v48
	v_fmamk_f32 v39, v39, 0x3e38aa3b, v48
	v_fmamk_f32 v40, v40, 0x3e38aa3b, v48
	v_fmamk_f32 v41, v41, 0x3e38aa3b, v48
	v_fmamk_f32 v42, v42, 0x3e38aa3b, v48
	v_fmamk_f32 v43, v43, 0x3e38aa3b, v48
	v_fmamk_f32 v44, v44, 0x3e38aa3b, v48
	v_fmamk_f32 v45, v45, 0x3e38aa3b, v48
	v_fmamk_f32 v46, v46, 0x3e38aa3b, v48
	v_fmac_f32_e32 v49, 0x3e38aa3b, v47
	v_exp_f32_e32 v115, v32
	v_exp_f32_e32 v124, v33
	v_exp_f32_e32 v125, v34
	v_exp_f32_e32 v126, v35
	v_exp_f32_e32 v127, v36
	v_exp_f32_e32 v160, v37
	v_exp_f32_e32 v161, v38
	v_exp_f32_e32 v162, v39
	v_exp_f32_e32 v116, v40
	v_exp_f32_e32 v117, v41
	v_exp_f32_e32 v118, v42
	v_exp_f32_e32 v119, v43
	v_exp_f32_e32 v120, v44
	v_exp_f32_e32 v121, v45
	v_exp_f32_e32 v122, v46
	v_exp_f32_e32 v123, v49
	v_pk_fma_f32 v[166:167], v[30:31], s[8:9], v[48:49] op_sel_hi:[1,0,0]
	v_pk_fma_f32 v[168:169], v[28:29], s[8:9], v[48:49] op_sel_hi:[1,0,0]
	v_pk_fma_f32 v[170:171], v[26:27], s[8:9], v[48:49] op_sel_hi:[1,0,0]
	v_pk_fma_f32 v[172:173], v[24:25], s[8:9], v[48:49] op_sel_hi:[1,0,0]
	v_pk_fma_f32 v[174:175], v[22:23], s[8:9], v[48:49] op_sel_hi:[1,0,0]
	v_pk_fma_f32 v[176:177], v[20:21], s[8:9], v[48:49] op_sel_hi:[1,0,0]
	v_pk_fma_f32 v[178:179], v[18:19], s[8:9], v[48:49] op_sel_hi:[1,0,0]
	v_pk_fma_f32 v[180:181], v[16:17], s[8:9], v[48:49] op_sel_hi:[1,0,0]
	v_or3_b32 v132, v186, v59, s1
	v_mov_b64_e32 v[30:31], v[14:15]
	v_mov_b64_e32 v[46:47], v[14:15]
	v_mov_b64_e32 v[62:63], v[14:15]
	v_lshl_add_u32 v223, v131, 2, s33
	v_lshlrev_b64 v[158:159], 1, v[132:133]
	v_mov_b32_e32 v132, 0
	v_mov_b64_e32 v[28:29], v[12:13]
	v_mov_b64_e32 v[26:27], v[10:11]
	v_mov_b64_e32 v[24:25], v[8:9]
	v_mov_b64_e32 v[22:23], v[6:7]
	v_mov_b64_e32 v[20:21], v[4:5]
	v_mov_b64_e32 v[18:19], v[2:3]
	v_mov_b64_e32 v[16:17], v[0:1]
	v_mov_b64_e32 v[44:45], v[12:13]
	v_mov_b64_e32 v[42:43], v[10:11]
	v_mov_b64_e32 v[40:41], v[8:9]
	v_mov_b64_e32 v[38:39], v[6:7]
	v_mov_b64_e32 v[36:37], v[4:5]
	v_mov_b64_e32 v[34:35], v[2:3]
	v_mov_b64_e32 v[32:33], v[0:1]
	v_mov_b64_e32 v[60:61], v[12:13]
	v_mov_b64_e32 v[58:59], v[10:11]
	v_mov_b64_e32 v[56:57], v[8:9]
	v_mov_b64_e32 v[54:55], v[6:7]
	v_mov_b64_e32 v[52:53], v[4:5]
	v_mov_b64_e32 v[50:51], v[2:3]
	v_mov_b64_e32 v[48:49], v[0:1]
	s_mov_b32 s37, 1
	.p2align	6

.LBB0_1077:
	v_readlane_b32 s2, v255, 9
	s_cmp_lg_u32 s2, 16
	s_cbranch_scc0 .LBB0_1071
	.p2align	6

.LBB0_1115:
	ds_read_b128 v[126:129], v217
	ds_read_b128 v[130:133], v207
	ds_read_b128 v[134:137], v207 offset:4352
	v_add_u32_e32 v125, v215, v160
	s_waitcnt lgkmcnt(0)
	v_mul_f32_e32 v0, 0x3fb8aa3b, v0
	v_exp_f32_e32 v0, v0
	v_mfma_f32_16x16x32_bf16 v[130:133], v[130:133], v[126:129], 0
	s_add_i32 s15, s19, 0xffffffa0
	s_add_i32 s14, s20, 0
	v_mfma_f32_16x16x32_bf16 v[126:129], v[134:137], v[126:129], 0
	ds_read_b128 v[134:137], v217 offset:64
	ds_read_b128 v[138:141], v207 offset:64
	s_waitcnt lgkmcnt(0)
	v_mfma_f32_16x16x32_bf16 v[130:133], v[138:141], v[134:137], v[130:133]
	ds_read_b128 v[138:141], v207 offset:4416
	s_waitcnt lgkmcnt(0)
	v_mfma_f32_16x16x32_bf16 v[126:129], v[138:141], v[134:137], v[126:129]
	ds_read_b128 v[134:137], v217 offset:128
	ds_read_b128 v[138:141], v207 offset:128
	s_waitcnt lgkmcnt(0)
	v_mfma_f32_16x16x32_bf16 v[130:133], v[138:141], v[134:137], v[130:133]
	ds_read_b128 v[138:141], v207 offset:4480
	s_waitcnt lgkmcnt(0)
	v_mfma_f32_16x16x32_bf16 v[126:129], v[138:141], v[134:137], v[126:129]
	ds_read_b128 v[134:137], v217 offset:192
	ds_read_b128 v[138:141], v207 offset:192
	s_waitcnt lgkmcnt(0)
	v_mfma_f32_16x16x32_bf16 v[130:133], v[138:141], v[134:137], v[130:133]
	ds_read_b128 v[138:141], v207 offset:4544
	s_waitcnt lgkmcnt(0)
	v_mfma_f32_16x16x32_bf16 v[126:129], v[138:141], v[134:137], v[126:129]
	v_add_u32_e32 v136, v164, v169
	ds_read_b128 v[138:141], v125 offset:17408
	ds_read_b128 v[142:145], v136
	s_nop 1
	v_pk_mul_f32 v[132:133], v[0:1], v[132:133] op_sel_hi:[0,1]
	v_pk_mul_f32 v[130:131], v[0:1], v[130:131] op_sel_hi:[0,1]
	s_nop 0
	v_pk_mul_f32 v[128:129], v[0:1], v[128:129] op_sel_hi:[0,1]
	v_pk_mul_f32 v[126:127], v[0:1], v[126:127] op_sel_hi:[0,1]
	s_waitcnt lgkmcnt(0)
	v_mfma_f32_16x16x32_bf16 v[130:133], v[142:145], v[138:141], v[130:133]
	ds_read_b128 v[142:145], v136 offset:4352
	v_add_u32_e32 v137, v164, v213
	s_waitcnt lgkmcnt(0)
	v_mfma_f32_16x16x32_bf16 v[126:129], v[142:145], v[138:141], v[126:129]
	ds_read_b128 v[138:141], v125 offset:17472
	ds_read_b128 v[142:145], v136 offset:64
	s_waitcnt lgkmcnt(0)
	v_mfma_f32_16x16x32_bf16 v[130:133], v[142:145], v[138:141], v[130:133]
	ds_read_b128 v[142:145], v136 offset:4416
	s_waitcnt lgkmcnt(0)
	v_mfma_f32_16x16x32_bf16 v[126:129], v[142:145], v[138:141], v[126:129]
	ds_read_b128 v[138:141], v125 offset:17536
	ds_read_b128 v[142:145], v136 offset:128
	s_waitcnt lgkmcnt(0)
	v_mfma_f32_16x16x32_bf16 v[130:133], v[142:145], v[138:141], v[130:133]
	ds_read_b128 v[142:145], v136 offset:4480
	s_waitcnt lgkmcnt(0)
	v_mfma_f32_16x16x32_bf16 v[126:129], v[142:145], v[138:141], v[126:129]
	ds_read_b128 v[138:141], v125 offset:17600
	ds_read_b128 v[142:145], v136 offset:192
	ds_read_u16 v134, v221
	s_waitcnt lgkmcnt(0)
	v_lshlrev_b32_e32 v134, 16, v134
	v_mfma_f32_16x16x32_bf16 v[130:133], v[142:145], v[138:141], v[130:133]
	ds_read_b128 v[142:145], v136 offset:4544
	s_waitcnt lgkmcnt(0)
	v_mfma_f32_16x16x32_bf16 v[126:129], v[142:145], v[138:141], v[126:129]
	s_waitcnt vmcnt(0)
	s_nop 3
	v_fma_f32 v130, v124, v134, v130
	ds_read_u16 v134, v221 offset:272
	s_waitcnt lgkmcnt(0)
	v_lshlrev_b32_e32 v134, 16, v134
	v_fma_f32 v131, v124, v134, v131
	ds_read_u16 v134, v221 offset:544
	s_waitcnt lgkmcnt(0)
	v_lshlrev_b32_e32 v134, 16, v134
	v_fma_f32 v132, v124, v134, v132
	ds_read_u16 v134, v221 offset:816
	v_cvt_pk_bf16_f32 v130, v130, v131
	s_waitcnt lgkmcnt(0)
	v_lshlrev_b32_e32 v134, 16, v134
	v_fmac_f32_e32 v133, v124, v134
	v_cvt_pk_bf16_f32 v131, v132, v133
	buffer_store_dwordx2 v[130:131], v216, s[8:11], s15 offen
	ds_read_u16 v130, v221 offset:4352
	s_sub_i32 s15, s19, 64
	s_waitcnt lgkmcnt(0)
	v_lshlrev_b32_e32 v130, 16, v130
	v_fma_f32 v126, v124, v130, v126
	ds_read_u16 v130, v221 offset:4624
	s_waitcnt lgkmcnt(0)
	v_lshlrev_b32_e32 v130, 16, v130
	v_fma_f32 v127, v124, v130, v127
	ds_read_u16 v130, v221 offset:4896
	s_waitcnt lgkmcnt(0)
	v_lshlrev_b32_e32 v130, 16, v130
	v_fma_f32 v128, v124, v130, v128
	ds_read_u16 v130, v221 offset:5168
	v_cvt_pk_bf16_f32 v126, v126, v127
	s_waitcnt lgkmcnt(0)
	v_lshlrev_b32_e32 v130, 16, v130
	v_fmac_f32_e32 v129, v124, v130
	v_cvt_pk_bf16_f32 v127, v128, v129
	buffer_store_dwordx2 v[126:127], v216, s[8:11], s15 offen
	ds_read_b128 v[126:129], v217
	ds_read_b128 v[130:133], v207 offset:8704
	ds_read_b128 v[138:141], v207 offset:13056
	s_waitcnt lgkmcnt(1)
	v_mfma_f32_16x16x32_bf16 v[130:133], v[130:133], v[126:129], 0
	s_sub_i32 s15, s19, 32
	s_and_b64 vcc, s[4:5], exec
	s_waitcnt lgkmcnt(0)
	v_mfma_f32_16x16x32_bf16 v[126:129], v[138:141], v[126:129], 0
	ds_read_b128 v[138:141], v217 offset:64
	ds_read_b128 v[142:145], v207 offset:8768
	s_waitcnt lgkmcnt(0)
	v_mfma_f32_16x16x32_bf16 v[130:133], v[142:145], v[138:141], v[130:133]
	ds_read_b128 v[142:145], v207 offset:13120
	s_waitcnt lgkmcnt(0)
	v_mfma_f32_16x16x32_bf16 v[126:129], v[142:145], v[138:141], v[126:129]
	ds_read_b128 v[138:141], v217 offset:128
	ds_read_b128 v[142:145], v207 offset:8832
	s_waitcnt lgkmcnt(0)
	v_mfma_f32_16x16x32_bf16 v[130:133], v[142:145], v[138:141], v[130:133]
	ds_read_b128 v[142:145], v207 offset:13184
	s_waitcnt lgkmcnt(0)
	v_mfma_f32_16x16x32_bf16 v[126:129], v[142:145], v[138:141], v[126:129]
	ds_read_b128 v[138:141], v217 offset:192
	ds_read_b128 v[142:145], v207 offset:8896
	s_waitcnt lgkmcnt(0)
	v_mfma_f32_16x16x32_bf16 v[130:133], v[142:145], v[138:141], v[130:133]
	ds_read_b128 v[142:145], v207 offset:13248
	s_waitcnt lgkmcnt(0)
	v_mfma_f32_16x16x32_bf16 v[126:129], v[142:145], v[138:141], v[126:129]
	ds_read_b128 v[138:141], v125 offset:17408
	ds_read_b128 v[142:145], v136 offset:8704
	s_nop 2
	v_pk_mul_f32 v[132:133], v[0:1], v[132:133] op_sel_hi:[0,1]
	v_pk_mul_f32 v[130:131], v[0:1], v[130:131] op_sel_hi:[0,1]
	s_nop 0
	v_pk_mul_f32 v[128:129], v[0:1], v[128:129] op_sel_hi:[0,1]
	v_pk_mul_f32 v[126:127], v[0:1], v[126:127] op_sel_hi:[0,1]
	s_waitcnt lgkmcnt(0)
	v_mfma_f32_16x16x32_bf16 v[130:133], v[142:145], v[138:141], v[130:133]
	ds_read_b128 v[142:145], v136 offset:13056
	s_waitcnt lgkmcnt(0)
	v_mfma_f32_16x16x32_bf16 v[126:129], v[142:145], v[138:141], v[126:129]
	ds_read_b128 v[138:141], v125 offset:17472
	ds_read_b128 v[142:145], v136 offset:8768
	s_waitcnt lgkmcnt(0)
	v_mfma_f32_16x16x32_bf16 v[130:133], v[142:145], v[138:141], v[130:133]
	ds_read_b128 v[142:145], v136 offset:13120
	s_waitcnt lgkmcnt(0)
	v_mfma_f32_16x16x32_bf16 v[126:129], v[142:145], v[138:141], v[126:129]
	ds_read_b128 v[138:141], v125 offset:17536
	ds_read_b128 v[142:145], v136 offset:8832
	s_waitcnt lgkmcnt(0)
	v_mfma_f32_16x16x32_bf16 v[130:133], v[142:145], v[138:141], v[130:133]
	ds_read_b128 v[142:145], v136 offset:13184
	s_waitcnt lgkmcnt(0)
	v_mfma_f32_16x16x32_bf16 v[126:129], v[142:145], v[138:141], v[126:129]
	ds_read_b128 v[138:141], v125 offset:17600
	ds_read_b128 v[142:145], v136 offset:8896
	ds_read_u16 v0, v221 offset:8704
	ds_read_u16 v125, v221 offset:8976
	s_waitcnt lgkmcnt(2)
	v_mfma_f32_16x16x32_bf16 v[130:133], v[142:145], v[138:141], v[130:133]
	ds_read_b128 v[142:145], v136 offset:13248
	s_waitcnt lgkmcnt(2)
	v_lshlrev_b32_e32 v0, 16, v0
	s_waitcnt lgkmcnt(1)
	v_lshlrev_b32_e32 v125, 16, v125
	s_nop 2
	v_fma_f32 v0, v124, v0, v130
	ds_read_u16 v130, v221 offset:9248
	v_fma_f32 v125, v124, v125, v131
	s_waitcnt lgkmcnt(1)
	v_mfma_f32_16x16x32_bf16 v[126:129], v[142:145], v[138:141], v[126:129]
	s_waitcnt lgkmcnt(0)
	v_lshlrev_b32_e32 v130, 16, v130
	v_fma_f32 v131, v124, v130, v132
	ds_read_u16 v130, v221 offset:9520
	s_waitcnt lgkmcnt(0)
	v_lshlrev_b32_e32 v130, 16, v130
	v_fmac_f32_e32 v133, v124, v130
	v_cvt_pk_bf16_f32 v130, v0, v125
	v_cvt_pk_bf16_f32 v131, v131, v133
	ds_read_u16 v0, v221 offset:13056
	ds_read_u16 v125, v221 offset:13328
	buffer_store_dwordx2 v[130:131], v216, s[8:11], s15 offen
	s_mov_b32 s15, 0x223fc
	s_cselect_b32 s15, s15, 0x22200
	s_waitcnt lgkmcnt(1)
	v_lshlrev_b32_e32 v0, 16, v0
	s_waitcnt lgkmcnt(0)
	v_lshlrev_b32_e32 v125, 16, v125
	v_fma_f32 v0, v124, v0, v126
	v_fma_f32 v125, v124, v125, v127
	ds_read_u16 v126, v221 offset:13600
	ds_read_u16 v127, v221 offset:13872
	s_add_i32 s14, s14, s15
	s_add_i32 s18, s18, 0x40000
	s_waitcnt lgkmcnt(1)
	v_lshlrev_b32_e32 v126, 16, v126
	s_waitcnt lgkmcnt(0)
	v_lshlrev_b32_e32 v127, 16, v127
	v_fma_f32 v126, v124, v126, v128
	v_fmac_f32_e32 v129, v124, v127
	v_cvt_pk_bf16_f32 v124, v0, v125
	v_mov_b32_e32 v0, s14
	v_cvt_pk_bf16_f32 v125, v126, v129
	ds_read_b32 v0, v0
	buffer_store_dwordx2 v[124:125], v216, s[8:11], s19 offen
	s_waitcnt lgkmcnt(0)
	v_mul_f32_e32 v0, 0x3fb8aa3b, v0
	v_exp_f32_e32 v0, v0
	s_nop 0
	v_pk_mul_f32 v[122:123], v[122:123], v[0:1] op_sel_hi:[1,0]
	v_pk_mul_f32 v[120:121], v[120:121], v[0:1] op_sel_hi:[1,0]
	v_pk_mul_f32 v[118:119], v[118:119], v[0:1] op_sel_hi:[1,0]
	v_pk_mul_f32 v[116:117], v[116:117], v[0:1] op_sel_hi:[1,0]
	v_pk_mul_f32 v[114:115], v[114:115], v[0:1] op_sel_hi:[1,0]
	v_pk_mul_f32 v[112:113], v[112:113], v[0:1] op_sel_hi:[1,0]
	v_pk_mul_f32 v[110:111], v[110:111], v[0:1] op_sel_hi:[1,0]
	v_pk_mul_f32 v[108:109], v[108:109], v[0:1] op_sel_hi:[1,0]
	v_add_u32_e32 v0, s20, v204
	v_add_u32_e32 v128, 0x22400, v0
	ds_read_b128 v[124:127], v137 offset:52224
	ds_read_b128 v[128:131], v128
	v_add_u32_e32 v132, 0x22410, v0
	ds_read_b128 v[132:135], v132
	s_addk_i32 s20, 0x600
	s_waitcnt lgkmcnt(2)
	v_lshlrev_b32_e32 v138, 16, v124
	v_and_b32_e32 v124, 0xffff0000, v124
	s_waitcnt lgkmcnt(1)
	v_mul_f32_e32 v128, v128, v138
	v_mul_f32_e32 v124, v129, v124
	v_cvt_pk_bf16_f32 v124, v128, v124
	v_lshlrev_b32_e32 v128, 16, v125
	v_and_b32_e32 v125, 0xffff0000, v125
	v_mul_f32_e32 v128, v130, v128
	v_mul_f32_e32 v125, v131, v125
	v_cvt_pk_bf16_f32 v125, v128, v125
	v_lshlrev_b32_e32 v128, 16, v126
	v_and_b32_e32 v126, 0xffff0000, v126
	s_waitcnt lgkmcnt(0)
	v_mul_f32_e32 v128, v132, v128
	v_mul_f32_e32 v126, v133, v126
	v_cvt_pk_bf16_f32 v126, v128, v126
	v_lshlrev_b32_e32 v128, 16, v127
	v_and_b32_e32 v127, 0xffff0000, v127
	v_mul_f32_e32 v128, v134, v128
	v_mul_f32_e32 v127, v135, v127
	v_cvt_pk_bf16_f32 v127, v128, v127
	ds_read_b128 v[128:131], v136
	v_add_u32_e32 v132, 0x22490, v0
	s_waitcnt lgkmcnt(0)
	v_mfma_f32_16x16x32_bf16 v[120:123], v[124:127], v[128:131], v[120:123]
	ds_read_b128 v[128:131], v136 offset:4352
	ds_read_b128 v[132:135], v132
	s_add_u32 s16, s16, 4
	s_waitcnt lgkmcnt(1)
	v_mfma_f32_16x16x32_bf16 v[116:119], v[124:127], v[128:131], v[116:119]
	ds_read_b128 v[128:131], v136 offset:8704
	s_addc_u32 s17, s17, 0
	s_addk_i32 s19, 0x80
	s_waitcnt lgkmcnt(0)
	v_mfma_f32_16x16x32_bf16 v[112:115], v[124:127], v[128:131], v[112:115]
	ds_read_b128 v[128:131], v136 offset:13056
	s_cmpk_eq_i32 s20, 0x1800
	s_waitcnt lgkmcnt(0)
	v_mfma_f32_16x16x32_bf16 v[108:111], v[124:127], v[128:131], v[108:111]
	ds_read_b128 v[124:127], v137 offset:52288
	v_add_u32_e32 v128, 0x22480, v0
	ds_read_b128 v[128:131], v128
	s_waitcnt lgkmcnt(1)
	v_lshlrev_b32_e32 v138, 16, v124
	v_and_b32_e32 v124, 0xffff0000, v124
	s_waitcnt lgkmcnt(0)
	v_mul_f32_e32 v128, v128, v138
	v_mul_f32_e32 v124, v129, v124
	v_cvt_pk_bf16_f32 v124, v128, v124
	v_lshlrev_b32_e32 v128, 16, v125
	v_and_b32_e32 v125, 0xffff0000, v125
	v_mul_f32_e32 v128, v130, v128
	v_mul_f32_e32 v125, v131, v125
	v_cvt_pk_bf16_f32 v125, v128, v125
	v_lshlrev_b32_e32 v128, 16, v126
	v_and_b32_e32 v126, 0xffff0000, v126
	v_mul_f32_e32 v128, v132, v128
	v_mul_f32_e32 v126, v133, v126
	v_cvt_pk_bf16_f32 v126, v128, v126
	v_lshlrev_b32_e32 v128, 16, v127
	v_and_b32_e32 v127, 0xffff0000, v127
	v_mul_f32_e32 v128, v134, v128
	v_mul_f32_e32 v127, v135, v127
	v_cvt_pk_bf16_f32 v127, v128, v127
	ds_read_b128 v[128:131], v136 offset:64
	v_add_u32_e32 v132, 0x22510, v0
	s_waitcnt lgkmcnt(0)
	v_mfma_f32_16x16x32_bf16 v[120:123], v[124:127], v[128:131], v[120:123]
	ds_read_b128 v[128:131], v136 offset:4416
	ds_read_b128 v[132:135], v132
	s_waitcnt lgkmcnt(1)
	v_mfma_f32_16x16x32_bf16 v[116:119], v[124:127], v[128:131], v[116:119]
	ds_read_b128 v[128:131], v136 offset:8768
	s_waitcnt lgkmcnt(0)
	v_mfma_f32_16x16x32_bf16 v[112:115], v[124:127], v[128:131], v[112:115]
	ds_read_b128 v[128:131], v136 offset:13120
	s_waitcnt lgkmcnt(0)
	v_mfma_f32_16x16x32_bf16 v[108:111], v[124:127], v[128:131], v[108:111]
	ds_read_b128 v[124:127], v137 offset:52352
	v_add_u32_e32 v128, 0x22500, v0
	ds_read_b128 v[128:131], v128
	s_waitcnt lgkmcnt(1)
	v_lshlrev_b32_e32 v138, 16, v124
	v_and_b32_e32 v124, 0xffff0000, v124
	s_waitcnt lgkmcnt(0)
	v_mul_f32_e32 v128, v128, v138
	v_mul_f32_e32 v124, v129, v124
	v_cvt_pk_bf16_f32 v124, v128, v124
	v_lshlrev_b32_e32 v128, 16, v125
	v_and_b32_e32 v125, 0xffff0000, v125
	v_mul_f32_e32 v128, v130, v128
	v_mul_f32_e32 v125, v131, v125
	v_cvt_pk_bf16_f32 v125, v128, v125
	v_lshlrev_b32_e32 v128, 16, v126
	v_and_b32_e32 v126, 0xffff0000, v126
	v_mul_f32_e32 v128, v132, v128
	v_mul_f32_e32 v126, v133, v126
	v_cvt_pk_bf16_f32 v126, v128, v126
	v_lshlrev_b32_e32 v128, 16, v127
	v_and_b32_e32 v127, 0xffff0000, v127
	v_mul_f32_e32 v128, v134, v128
	v_mul_f32_e32 v127, v135, v127
	v_cvt_pk_bf16_f32 v127, v128, v127
	ds_read_b128 v[128:131], v136 offset:128
	s_waitcnt lgkmcnt(0)
	v_mfma_f32_16x16x32_bf16 v[120:123], v[124:127], v[128:131], v[120:123]
	ds_read_b128 v[128:131], v136 offset:4480
	s_waitcnt lgkmcnt(0)
	v_mfma_f32_16x16x32_bf16 v[116:119], v[124:127], v[128:131], v[116:119]
	ds_read_b128 v[128:131], v136 offset:8832
	s_waitcnt lgkmcnt(0)
	v_mfma_f32_16x16x32_bf16 v[112:115], v[124:127], v[128:131], v[112:115]
	ds_read_b128 v[128:131], v136 offset:13184
	s_waitcnt lgkmcnt(0)
	v_mfma_f32_16x16x32_bf16 v[108:111], v[124:127], v[128:131], v[108:111]
	ds_read_b128 v[124:127], v137 offset:52416
	v_add_u32_e32 v128, 0x22580, v0
	ds_read_b128 v[128:131], v128
	v_add_u32_e32 v0, 0x22590, v0
	ds_read_b128 v[132:135], v0
	s_waitcnt lgkmcnt(2)
	v_lshlrev_b32_e32 v0, 16, v124
	v_and_b32_e32 v124, 0xffff0000, v124
	s_waitcnt lgkmcnt(1)
	v_mul_f32_e32 v124, v129, v124
	v_mul_f32_e32 v0, v128, v0
	v_cvt_pk_bf16_f32 v138, v0, v124
	v_and_b32_e32 v124, 0xffff0000, v125
	v_lshlrev_b32_e32 v0, 16, v125
	v_mul_f32_e32 v124, v131, v124
	v_mul_f32_e32 v0, v130, v0
	v_cvt_pk_bf16_f32 v139, v0, v124
	v_and_b32_e32 v124, 0xffff0000, v126
	v_lshlrev_b32_e32 v0, 16, v126
	s_waitcnt lgkmcnt(0)
	v_mul_f32_e32 v124, v133, v124
	v_mul_f32_e32 v0, v132, v0
	v_cvt_pk_bf16_f32 v140, v0, v124
	v_and_b32_e32 v124, 0xffff0000, v127
	v_lshlrev_b32_e32 v0, 16, v127
	v_mul_f32_e32 v124, v135, v124
	v_mul_f32_e32 v0, v134, v0
	v_cvt_pk_bf16_f32 v141, v0, v124
	ds_read_b128 v[124:127], v136 offset:192
	s_waitcnt lgkmcnt(0)
	v_mfma_f32_16x16x32_bf16 v[124:127], v[138:141], v[124:127], v[120:123]
	s_nop 2
	ds_read_b128 v[120:123], v136 offset:4544
	s_waitcnt lgkmcnt(0)
	v_mfma_f32_16x16x32_bf16 v[128:131], v[138:141], v[120:123], v[116:119]
	s_nop 2
	ds_read_b128 v[116:119], v136 offset:8896
	s_waitcnt lgkmcnt(0)
	v_mfma_f32_16x16x32_bf16 v[132:135], v[138:141], v[116:119], v[112:115]
	s_nop 2
	ds_read_b128 v[112:115], v136 offset:13248
	s_waitcnt lgkmcnt(0)
	v_mfma_f32_16x16x32_bf16 v[136:139], v[138:141], v[112:115], v[108:111]
	s_cbranch_scc1 .LBB0_1141
	.p2align	6
